# prompt attention: loop-invariant q-norm gain vector loaded once per item instead of two load+wait pairs per query pass; in-loop vmcnt(0) waits dropped
# speedup vs baseline: 1.0005x; 1.0005x over previous
; __device__ __forceinline__ void attn_item(const Args& a, LAS unsigned char* lds, int layer, bool is_sample, int b, int c, int kvh, int seq_row0, int nchunks, bf16_t* proj, const int tid) {
;     ...
;     const float sink = a.in[22][layer * NQH + hq] * 1.4426950408889634f;
;     const float* qng = a.in[20] + layer * 64;
;     const int kmin = is_sample ? 0 : (2 - c) * 64;
; #pragma unroll 1
;     for (int sub = 0; sub < 2; ++sub) {
;         const int ql = (wave & 1) * 32 + sub * 16 + fr;
;         bf16_t* qp = proj + (size_t)(row0 + ql) * PN + C_Q + hq * 64;
;         bf16x8 qf[2];
;         {
;             float qv[2][8]; float ss = 0.f;
; #pragma unroll
;             for (int ks = 0; ks < 2; ++ks) { const u32x4 w = sub ? qraw[1][ks] : qraw[0][ks];
;                 qv[ks][0] = bflo(w.x); qv[ks][1] = bfhi(w.x); qv[ks][2] = bflo(w.y); qv[ks][3] = bfhi(w.y); qv[ks][4] = bflo(w.z); qv[ks][5] = bfhi(w.z); qv[ks][6] = bflo(w.w); qv[ks][7] = bfhi(w.w);
; #pragma unroll
;                 for (int e = 0; e < 8; ++e) ss += qv[ks][e] * qv[ks][e]; }
;             ss += __shfl_xor(ss, 16); ss += __shfl_xor(ss, 32);
;             const float rs = rsqrtf(ss * (1.f / 64.f) + EPS) * (0.125f * 1.4426950408889634f);
; #pragma unroll
;             for (int ks = 0; ks < 2; ++ks) { const f32x4 g0 = *(const f32x4*)(qng + 32 * ks + 8 * fq), g1 = *(const f32x4*)(qng + 32 * ks + 8 * fq + 4);
;                 u32x4 w; w.x = pk2(qv[ks][0] * rs * g0[0], qv[ks][1] * rs * g0[1]); w.y = pk2(qv[ks][2] * rs * g0[2], qv[ks][3] * rs * g0[3]);
;                 w.z = pk2(qv[ks][4] * rs * g1[0], qv[ks][5] * rs * g1[1]); w.w = pk2(qv[ks][6] * rs * g1[2], qv[ks][7] * rs * g1[3]);
;                 qf[ks] = __builtin_bit_cast(bf16x8, w); }
;         }
;         f32x4 sacc[12];
; #pragma unroll
;         for (int kb = 0; kb < 12; ++kb) { sacc[kb] = (f32x4){0.f, 0.f, 0.f, 0.f};
; #pragma unroll
;             for (int ks = 0; ks < 2; ++ks) { const bf16x8 av = *(const LAS bf16x8*)(lds + L_KS + (16 * kb + fr) * PK + (32 * ks + 8 * fq) * 2); sacc[kb] = mfma16(av, qf[ks], sacc[kb]); } }
;         float mx = sink;
; #pragma unroll
;         for (int kb = 0; kb < 12; ++kb)
; #pragma unroll
;             for (int j = 0; j < 4; ++j) { const int kl = 16 * kb + 4 * fq + j;
;                 const float s = sacc[kb][j] + bt[g * 256 + kl - 128 - ql + 191];
;                 sacc[kb][j] = s; mx = fmaxf(mx, s); }
.LBB0_475:
	s_or_b64 exec, exec, s[4:5]
	s_add_i32 s4, s39, s75
	s_ashr_i32 s5, s4, 31
	s_lshl_b64 s[4:5], s[4:5], 2
	s_add_u32 s4, s88, s4
	s_addc_u32 s5, s89, s5
	s_waitcnt lgkmcnt(0)
	s_barrier
	global_load_dword v19, v1, s[4:5]
	v_lshlrev_b32_e32 v0, 3, v42
	v_cmp_lt_i32_e32 vcc, v208, v203
	v_lshlrev_b32_e32 v18, 2, v42
	v_lshlrev_b32_e32 v0, 2, v0
	v_cndmask_b32_e32 v20, v201, v208, vcc
	v_cmp_lt_i32_e32 vcc, v209, v203
	v_lshrrev_b32_e32 v23, 1, v36
	v_lshl_add_u64 v[66:67], s[82:83], 0, v[0:1]
	global_load_dwordx4 v[216:219], v[66:67], off
	global_load_dwordx4 v[220:223], v[66:67], off offset:16
	global_load_dwordx4 v[224:227], v[66:67], off offset:128
	global_load_dwordx4 v[228:231], v[66:67], off offset:144
	v_cndmask_b32_e32 v21, v201, v209, vcc
	s_sub_i32 s6, 0x80, s38
	v_or_b32_e32 v0, 0x72, v18
	v_lshl_add_u32 v22, v42, 4, 0
	v_lshlrev_b32_e32 v93, 2, v20
	v_lshlrev_b32_e32 v94, 2, v21
	v_and_b32_e32 v20, 4, v23
	v_or_b32_e32 v21, 16, v18
	v_or_b32_e32 v25, 32, v18
	v_or_b32_e32 v26, 64, v18
	v_or_b32_e32 v27, 0x60, v18
	v_or_b32_e32 v28, 1, v18
	v_or_b32_e32 v29, 2, v18
	v_or_b32_e32 v30, 3, v18
	v_or_b32_e32 v31, 17, v18
	v_or_b32_e32 v32, 18, v18
	v_or_b32_e32 v33, 19, v18
	v_or_b32_e32 v34, 33, v18
	v_or_b32_e32 v35, 34, v18
	v_or_b32_e32 v36, 35, v18
	v_or_b32_e32 v37, 48, v18
	v_or_b32_e32 v38, 49, v18
	v_or_b32_e32 v39, 50, v18
	v_or_b32_e32 v40, 51, v18
	v_or_b32_e32 v42, 0x41, v18
	v_or_b32_e32 v43, 0x42, v18
	v_or_b32_e32 v44, 0x43, v18
	v_or_b32_e32 v45, 0x50, v18
	v_or_b32_e32 v46, 0x51, v18
	v_or_b32_e32 v47, 0x52, v18
	v_or_b32_e32 v48, 0x53, v18
	v_or_b32_e32 v49, 0x61, v18
	s_waitcnt vmcnt(11)
	v_or_b32_e32 v50, 0x62, v18
	v_or_b32_e32 v51, 0x63, v18
	v_or_b32_e32 v52, 0x70, v18
	v_or_b32_e32 v53, 0x71, v18
	v_cmp_gt_i32_e64 s[4:5], s6, v0
	v_or_b32_e32 v0, 0x73, v18
	s_movk_i32 s16, 0x190
	v_cmp_gt_i32_e64 s[38:39], s6, v18
	v_cmp_gt_i32_e64 s[40:41], s6, v28
	v_cmp_gt_i32_e64 s[42:43], s6, v29
	v_cmp_gt_i32_e64 s[44:45], s6, v30
	v_cmp_gt_i32_e64 s[46:47], s6, v21
	v_cmp_gt_i32_e64 s[48:49], s6, v31
	v_cmp_gt_i32_e64 s[50:51], s6, v32
	v_cmp_gt_i32_e64 s[52:53], s6, v33
	v_cmp_gt_i32_e64 s[54:55], s6, v25
	v_cmp_gt_i32_e64 s[56:57], s6, v34
	v_cmp_gt_i32_e64 s[58:59], s6, v35
	v_cmp_gt_i32_e64 s[60:61], s6, v36
	v_cmp_gt_i32_e64 s[62:63], s6, v37
	v_cmp_gt_i32_e64 s[64:65], s6, v38
	v_cmp_gt_i32_e64 s[66:67], s6, v39
	v_cmp_gt_i32_e64 s[68:69], s6, v40
	v_cmp_gt_i32_e64 s[70:71], s6, v26
	v_cmp_gt_i32_e64 s[72:73], s6, v42
	v_cmp_gt_i32_e64 s[74:75], s6, v43
	v_cmp_gt_i32_e64 s[76:77], s6, v44
	v_cmp_gt_i32_e64 s[78:79], s6, v45
	v_cmp_gt_i32_e64 s[80:81], s6, v46
	v_cmp_gt_i32_e64 s[82:83], s6, v47
	v_cmp_gt_i32_e64 s[84:85], s6, v48
	v_cmp_gt_i32_e64 s[86:87], s6, v27
	v_cmp_gt_i32_e64 s[88:89], s6, v49
	v_cmp_gt_i32_e64 s[90:91], s6, v50
	v_cmp_gt_i32_e64 s[92:93], s6, v51
	v_cmp_gt_i32_e64 s[94:95], s6, v52
	v_cmp_gt_i32_e64 s[96:97], s6, v53
	v_cmp_gt_i32_e64 s[6:7], s6, v0
	v_mad_u32_u24 v0, v41, s16, 0
	v_or_b32_e32 v21, 8, v20
	v_or_b32_e32 v25, 16, v20
	v_or_b32_e32 v27, 24, v20
	s_movk_i32 s16, 0x80
	v_bitop3_b32 v29, v18, v20, s16 bitop3:0x36
	s_movk_i32 s17, 0x90
	v_bitop3_b32 v31, v18, v21, s16 bitop3:0x36
	v_bitop3_b32 v33, v18, v25, s16 bitop3:0x36
	v_bitop3_b32 v35, v18, v27, s16 bitop3:0x36
	s_movk_i32 s16, 0xb0
	v_bitop3_b32 v30, v18, v20, s17 bitop3:0x36
	v_bitop3_b32 v32, v18, v21, s17 bitop3:0x36
	v_bitop3_b32 v34, v18, v25, s17 bitop3:0x36
	v_bitop3_b32 v36, v18, v27, s17 bitop3:0x36
	s_movk_i32 s17, 0xa0
	v_bitop3_b32 v38, v18, v20, s16 bitop3:0x36
	v_bitop3_b32 v40, v18, v21, s16 bitop3:0x36
	v_bitop3_b32 v42, v18, v25, s16 bitop3:0x36
	v_bitop3_b32 v44, v18, v27, s16 bitop3:0x36
	s_movk_i32 s16, 0x50
	v_mul_u32_u24_e32 v24, 0x90, v41
	v_bitop3_b32 v37, v18, v20, s17 bitop3:0x36
	v_bitop3_b32 v39, v18, v21, s17 bitop3:0x36
	v_bitop3_b32 v41, v18, v25, s17 bitop3:0x36
	v_bitop3_b32 v43, v18, v27, s17 bitop3:0x36
	v_bitop3_b32 v58, v18, v20, s16 bitop3:0x36
	v_bitop3_b32 v60, v18, v21, s16 bitop3:0x36
	v_bitop3_b32 v62, v18, v25, s16 bitop3:0x36
	v_bitop3_b32 v64, v18, v27, s16 bitop3:0x36
	s_movk_i32 s16, 0x60
	s_movk_i32 s17, 0x70
	s_waitcnt vmcnt(0)
; #define LAS __attribute__((address_space(3)))
; __device__ __forceinline__ void attn_item(const Args& a, LAS unsigned char* lds, int layer, bool is_sample, int b, int c, int kvh, int seq_row0, int nchunks, bf16_t* proj, const int tid) {
;     ...
;     const float sink = a.in[22][layer * NQH + hq] * 1.4426950408889634f;
;     const float* qng = a.in[20] + layer * 64;
;     const int kmin = is_sample ? 0 : (2 - c) * 64;
; #pragma unroll 1
;     for (int sub = 0; sub < 2; ++sub) {
;         const int ql = (wave & 1) * 32 + sub * 16 + fr;
;     ...
;             for (int db = 0; db < 4; ++db) { const LAS unsigned char* vr = lds + L_VT + (16 * db + fr) * PV; const int vkey = ((2 * db + (fr >> 3)) & 7) << 2;
;                 const u32x2 lo = *(const LAS u32x2*)(vr + ((32 * ks + 4 * fq) ^ vkey) * 2), hi = *(const LAS u32x2*)(vr + ((32 * ks + 16 + 4 * fq) ^ vkey) * 2);
	v_mul_f32_e32 v95, 0x3fb8aa3b, v19
	v_bitop3_b32 v19, v18, v23, 4 bitop3:0x78
	v_bitop3_b32 v23, v20, v18, 8 bitop3:0x36
	v_bitop3_b32 v26, v20, v18, 16 bitop3:0x36
	v_bitop3_b32 v28, v20, v18, 24 bitop3:0x36
	v_bitop3_b32 v45, v18, v20, 16 bitop3:0x36
	v_bitop3_b32 v46, v18, v21, 16 bitop3:0x36
	v_bitop3_b32 v47, v18, v20, 16 bitop3:0x14
	v_bitop3_b32 v48, v18, v27, 16 bitop3:0x36
	v_bitop3_b32 v49, v18, v20, 32 bitop3:0x36
	v_bitop3_b32 v50, v18, v20, 48 bitop3:0x36
	v_bitop3_b32 v51, v18, v21, 32 bitop3:0x36
	v_bitop3_b32 v52, v18, v21, 48 bitop3:0x36
	v_bitop3_b32 v53, v18, v25, 32 bitop3:0x36
	v_bitop3_b32 v54, v18, v25, 48 bitop3:0x36
	v_bitop3_b32 v55, v18, v27, 32 bitop3:0x36
	v_bitop3_b32 v56, v18, v27, 48 bitop3:0x36
	v_bitop3_b32 v57, v18, v20, 64 bitop3:0x36
	v_bitop3_b32 v59, v18, v21, 64 bitop3:0x36
	v_bitop3_b32 v61, v18, v25, 64 bitop3:0x36
	v_bitop3_b32 v63, v18, v27, 64 bitop3:0x36
	v_bitop3_b32 v65, v18, v20, s16 bitop3:0x36
	v_bitop3_b32 v20, v18, v20, s17 bitop3:0x36
	v_bitop3_b32 v68, v18, v21, s16 bitop3:0x36
	v_bitop3_b32 v21, v18, v21, s17 bitop3:0x36
	v_bitop3_b32 v69, v18, v25, s16 bitop3:0x36
	v_bitop3_b32 v25, v18, v25, s17 bitop3:0x36
	v_bitop3_b32 v70, v18, v27, s16 bitop3:0x36
	v_bitop3_b32 v27, v18, v27, s17 bitop3:0x36
	s_cmp_gt_u32 s21, 1
	v_lshlrev_b32_e32 v19, 1, v19
	v_lshlrev_b32_e32 v23, 1, v23
	v_lshlrev_b32_e32 v26, 1, v26
	v_lshlrev_b32_e32 v28, 1, v28
	v_lshlrev_b32_e32 v29, 1, v29
	v_lshlrev_b32_e32 v30, 1, v30
	v_lshlrev_b32_e32 v31, 1, v31
	v_lshlrev_b32_e32 v32, 1, v32
	v_lshlrev_b32_e32 v33, 1, v33
	v_lshlrev_b32_e32 v34, 1, v34
	v_lshlrev_b32_e32 v35, 1, v35
	v_lshlrev_b32_e32 v36, 1, v36
	v_lshlrev_b32_e32 v37, 1, v37
	v_lshlrev_b32_e32 v38, 1, v38
	v_lshlrev_b32_e32 v39, 1, v39
	v_lshlrev_b32_e32 v40, 1, v40
	v_lshlrev_b32_e32 v41, 1, v41
	v_lshlrev_b32_e32 v42, 1, v42
	v_lshlrev_b32_e32 v43, 1, v43
	v_lshlrev_b32_e32 v44, 1, v44
	v_lshlrev_b32_e32 v45, 1, v45
	v_lshlrev_b32_e32 v46, 1, v46
	v_lshlrev_b32_e32 v47, 1, v47
	v_lshlrev_b32_e32 v48, 1, v48
	v_lshlrev_b32_e32 v49, 1, v49
	v_lshlrev_b32_e32 v50, 1, v50
	v_lshlrev_b32_e32 v51, 1, v51
	v_lshlrev_b32_e32 v52, 1, v52
	v_lshlrev_b32_e32 v53, 1, v53
	v_lshlrev_b32_e32 v54, 1, v54
	v_lshlrev_b32_e32 v55, 1, v55
	v_lshlrev_b32_e32 v56, 1, v56
	v_lshlrev_b32_e32 v57, 1, v57
	v_lshlrev_b32_e32 v58, 1, v58
	v_lshlrev_b32_e32 v59, 1, v59
	v_lshlrev_b32_e32 v60, 1, v60
	v_lshlrev_b32_e32 v61, 1, v61
	v_lshlrev_b32_e32 v62, 1, v62
	v_lshlrev_b32_e32 v63, 1, v63
	v_lshlrev_b32_e32 v64, 1, v64
	v_lshlrev_b32_e32 v65, 1, v65
	v_lshlrev_b32_e32 v20, 1, v20
	v_lshlrev_b32_e32 v68, 1, v68
	v_lshlrev_b32_e32 v21, 1, v21
	v_lshlrev_b32_e32 v69, 1, v69
	v_lshlrev_b32_e32 v25, 1, v25
	v_lshlrev_b32_e32 v70, 1, v70
	v_lshlrev_b32_e32 v27, 1, v27
	s_mov_b32 s10, 0
	s_cselect_b64 s[14:15], -1, 0
	v_lshl_or_b32 v96, s20, 8, v18
	v_add_u32_e32 v97, v22, v24
	v_add_u32_e32 v98, v0, v19
	v_add_u32_e32 v99, v0, v45
	v_add_u32_e32 v100, v0, v23
	v_add_u32_e32 v101, v0, v46
	v_add_u32_e32 v102, v0, v26
	v_add_u32_e32 v103, v0, v47
	v_add_u32_e32 v104, v0, v28
	v_add_u32_e32 v105, v0, v48
	v_add_u32_e32 v106, v0, v49
	v_add_u32_e32 v107, v0, v50
	v_add_u32_e32 v108, v0, v51
	v_add_u32_e32 v109, v0, v52
	v_add_u32_e32 v110, v0, v53
	v_add_u32_e32 v111, v0, v54
	v_add_u32_e32 v112, v0, v55
	v_add_u32_e32 v113, v0, v56
	v_add_u32_e32 v114, v0, v57
	v_add_u32_e32 v115, v0, v58
	v_add_u32_e32 v116, v0, v59
	v_add_u32_e32 v117, v0, v60
	v_add_u32_e32 v118, v0, v61
	v_add_u32_e32 v119, v0, v62
	v_add_u32_e32 v120, v0, v63
	v_add_u32_e32 v121, v0, v64
	v_add_u32_e32 v122, v0, v65
	v_add_u32_e32 v123, v0, v20
	v_add_u32_e32 v124, v0, v68
	v_add_u32_e32 v125, v0, v21
	v_add_u32_e32 v126, v0, v69
	v_add_u32_e32 v127, v0, v25
	v_add_u32_e32 v128, v0, v70
	v_add_u32_e32 v129, v0, v27
	v_add_u32_e32 v130, v0, v29
	v_add_u32_e32 v131, v0, v30
	v_add_u32_e32 v132, v0, v31
	v_add_u32_e32 v133, v0, v32
	v_add_u32_e32 v134, v0, v33
	v_add_u32_e32 v135, v0, v34
	v_add_u32_e32 v136, v0, v35
	v_add_u32_e32 v137, v0, v36
	v_add_u32_e32 v138, v0, v37
	v_add_u32_e32 v139, v0, v38
	v_add_u32_e32 v140, v0, v39
	v_add_u32_e32 v141, v0, v40
	v_add_u32_e32 v142, v0, v41
	v_add_u32_e32 v143, v0, v42
	v_add_u32_e32 v144, v0, v43
	v_add_u32_e32 v145, v0, v44
	v_lshlrev_b32_e32 v0, 1, v18
	s_mov_b64 s[16:17], -1
	s_branch .LBB0_477

; #define LAS __attribute__((address_space(3)))
; __device__ __forceinline__ unsigned pk2(float lo, float hi) { unsigned r; asm("v_cvt_pk_bf16_f32 %0, %1, %2" : "=v"(r) : "v"(lo), "v"(hi)); return r; }
; __device__ __forceinline__ float bflo(unsigned w) { return __uint_as_float(w << 16); }
; __device__ __forceinline__ float bfhi(unsigned w) { return __uint_as_float(w & 0xffff0000u); }
; __device__ __forceinline__ f32x4 mfma16(bf16x8 a, bf16x8 b, f32x4 c) { return __builtin_amdgcn_mfma_f32_16x16x32_bf16(a, b, c, 0, 0, 0); }
; __device__ __forceinline__ void attn_item(const Args& a, LAS unsigned char* lds, int layer, bool is_sample, int b, int c, int kvh, int seq_row0, int nchunks, bf16_t* proj, const int tid) {
;     ...
;             for (int ks = 0; ks < 2; ++ks) { const u32x4 w = sub ? qraw[1][ks] : qraw[0][ks];
;                 qv[ks][0] = bflo(w.x); qv[ks][1] = bfhi(w.x); qv[ks][2] = bflo(w.y); qv[ks][3] = bfhi(w.y); qv[ks][4] = bflo(w.z); qv[ks][5] = bfhi(w.z); qv[ks][6] = bflo(w.w); qv[ks][7] = bfhi(w.w);
; #pragma unroll
;                 for (int e = 0; e < 8; ++e) ss += qv[ks][e] * qv[ks][e]; }
;             ss += __shfl_xor(ss, 16); ss += __shfl_xor(ss, 32);
;             const float rs = rsqrtf(ss * (1.f / 64.f) + EPS) * (0.125f * 1.4426950408889634f);
; #pragma unroll
;             for (int ks = 0; ks < 2; ++ks) { const f32x4 g0 = *(const f32x4*)(qng + 32 * ks + 8 * fq), g1 = *(const f32x4*)(qng + 32 * ks + 8 * fq + 4);
;                 u32x4 w; w.x = pk2(qv[ks][0] * rs * g0[0], qv[ks][1] * rs * g0[1]); w.y = pk2(qv[ks][2] * rs * g0[2], qv[ks][3] * rs * g0[3]);
;                 w.z = pk2(qv[ks][4] * rs * g1[0], qv[ks][5] * rs * g1[1]); w.w = pk2(qv[ks][6] * rs * g1[2], qv[ks][7] * rs * g1[3]);
;                 qf[ks] = __builtin_bit_cast(bf16x8, w); }
;         }
;         f32x4 sacc[12];
; #pragma unroll
;         for (int kb = 0; kb < 12; ++kb) { sacc[kb] = (f32x4){0.f, 0.f, 0.f, 0.f};
; #pragma unroll
;             for (int ks = 0; ks < 2; ++ks) { const bf16x8 av = *(const LAS bf16x8*)(lds + L_KS + (16 * kb + fr) * PK + (32 * ks + 8 * fq) * 2); sacc[kb] = mfma16(av, qf[ks], sacc[kb]); } }
.LBB0_477:
	v_cndmask_b32_e64 v21, v10, v2, s[16:17]
	v_cndmask_b32_e64 v20, v11, v3, s[16:17]
	v_and_b32_e32 v31, 0xffff0000, v21
	v_lshlrev_b32_e32 v30, 16, v21
	v_lshlrev_b32_e32 v32, 16, v20
	v_and_b32_e32 v33, 0xffff0000, v20
	v_mul_f32_e32 v20, v31, v31
	v_fmac_f32_e32 v20, v30, v30
	v_cndmask_b32_e64 v19, v12, v4, s[16:17]
	v_fmac_f32_e32 v20, v32, v32
	v_lshlrev_b32_e32 v39, 16, v19
	v_fmac_f32_e32 v20, v33, v33
	v_cndmask_b32_e64 v18, v13, v5, s[16:17]
	v_and_b32_e32 v40, 0xffff0000, v19
	v_fmac_f32_e32 v20, v39, v39
	v_lshlrev_b32_e32 v41, 16, v18
	v_and_b32_e32 v42, 0xffff0000, v18
	v_fmac_f32_e32 v20, v40, v40
	v_cndmask_b32_e64 v18, v14, v6, s[16:17]
	v_fmac_f32_e32 v20, v41, v41
	v_and_b32_e32 v34, 0xffff0000, v18
	v_lshlrev_b32_e32 v35, 16, v18
	v_fmac_f32_e32 v20, v42, v42
	v_cndmask_b32_e64 v23, v15, v7, s[16:17]
	v_pk_mul_f32 v[18:19], v[34:35], v[34:35]
	v_and_b32_e32 v36, 0xffff0000, v23
	v_add_f32_e32 v19, v19, v20
	v_lshlrev_b32_e32 v37, 16, v23
	v_cndmask_b32_e64 v22, v16, v8, s[16:17]
	v_add_f32_e32 v20, v18, v19
	v_pk_mul_f32 v[18:19], v[36:37], v[36:37]
	v_and_b32_e32 v28, 0xffff0000, v22
	v_add_f32_e32 v19, v19, v20
	v_lshlrev_b32_e32 v29, 16, v22
	v_cndmask_b32_e64 v21, v17, v9, s[16:17]
	v_add_f32_e32 v20, v18, v19
	v_pk_mul_f32 v[18:19], v[28:29], v[28:29]
	v_and_b32_e32 v26, 0xffff0000, v21
	v_add_f32_e32 v19, v19, v20
	v_lshlrev_b32_e32 v27, 16, v21
	v_add_f32_e32 v20, v18, v19
	v_pk_mul_f32 v[18:19], v[26:27], v[26:27]
	v_or_b32_e32 v146, s10, v92
	v_add_f32_e32 v19, v19, v20
	v_add_f32_e32 v18, v18, v19
	s_mov_b32 s10, 0x800000
	s_mov_b64 s[20:21], -1
	s_waitcnt lgkmcnt(0)
	v_mov_b32_e32 v19, v18
	v_mov_b32_e32 v250, v18
	s_nop 1
	v_permlane16_swap_b32_e32 v19, v250
	v_add_f32_e32 v18, v19, v250
	s_waitcnt lgkmcnt(0)
	v_mov_b32_e32 v19, v18
	v_mov_b32_e32 v250, v18
	s_nop 1
	v_permlane32_swap_b32_e32 v19, v250
	v_add_f32_e32 v18, v19, v250
	v_fmamk_f32 v18, v18, 0x3c800000, v167
	v_cmp_gt_f32_e32 vcc, s10, v18
	v_mul_f32_e32 v19, 0x4b800000, v18
	s_nop 0
	v_cndmask_b32_e32 v18, v18, v19, vcc
	v_rsq_f32_e32 v18, v18
	s_nop 0
	v_mul_f32_e32 v19, 0x45800000, v18
	v_cndmask_b32_e32 v18, v18, v19, vcc
	v_mul_f32_e32 v38, 0x3e38aa3b, v18
	v_mov_b64_e32 v[18:19], v[220:221]
	v_mov_b64_e32 v[20:21], v[222:223]
	v_mov_b64_e32 v[22:23], v[216:217]
	v_mov_b64_e32 v[24:25], v[218:219]
	v_mul_f32_e32 v30, v38, v30
	v_mul_f32_e32 v35, v38, v35
	v_mul_f32_e32 v34, v38, v34
	s_andn2_b64 vcc, exec, s[14:15]
	v_mul_f32_e32 v22, v22, v30
	v_mul_f32_e32 v30, v38, v31
	v_mul_f32_e32 v23, v23, v30
	v_cvt_pk_bf16_f32 v30, v22, v23
	v_mul_f32_e32 v22, v38, v32
	v_mul_f32_e32 v22, v24, v22
	v_mul_f32_e32 v23, v38, v33
	v_mul_f32_e32 v23, v25, v23
	v_cvt_pk_bf16_f32 v31, v22, v23
	v_mul_f32_e32 v22, v38, v39
	v_mul_f32_e32 v18, v18, v22
	v_mul_f32_e32 v22, v38, v40
	v_mul_f32_e32 v19, v19, v22
	v_cvt_pk_bf16_f32 v32, v18, v19
	v_mul_f32_e32 v18, v38, v41
	v_mul_f32_e32 v19, v38, v42
	v_mul_f32_e32 v18, v20, v18
	v_mul_f32_e32 v19, v21, v19
	v_cvt_pk_bf16_f32 v33, v18, v19
	v_mov_b64_e32 v[18:19], v[228:229]
	v_mov_b64_e32 v[20:21], v[230:231]
	v_mov_b64_e32 v[22:23], v[224:225]
	v_mov_b64_e32 v[24:25], v[226:227]
	ds_read_b128 v[74:77], v97 offset:23104
	v_mul_f32_e32 v22, v22, v35
	v_mul_f32_e32 v23, v23, v34
	v_cvt_pk_bf16_f32 v34, v22, v23
	v_mul_f32_e32 v22, v38, v37
	v_mul_f32_e32 v22, v24, v22
	v_mul_f32_e32 v23, v38, v36
	v_mul_f32_e32 v23, v25, v23
	v_cvt_pk_bf16_f32 v35, v22, v23
	v_mul_f32_e32 v22, v38, v29
	v_mul_f32_e32 v18, v18, v22
	v_mul_f32_e32 v22, v38, v28
	v_mul_f32_e32 v19, v19, v22
	v_cvt_pk_bf16_f32 v36, v18, v19
	v_mul_f32_e32 v18, v38, v27
	v_mul_f32_e32 v19, v38, v26
	v_mul_f32_e32 v18, v20, v18
	v_mul_f32_e32 v19, v21, v19
	v_cvt_pk_bf16_f32 v37, v18, v19
	ds_read_b128 v[18:21], v97
	ds_read_b128 v[22:25], v97 offset:64
	s_waitcnt lgkmcnt(1)
	v_mfma_f32_16x16x32_bf16 v[18:21], v[18:21], v[30:33], 0
	ds_read_b128 v[26:29], v97 offset:20800
	s_waitcnt lgkmcnt(1)
	v_mfma_f32_16x16x32_bf16 v[62:65], v[22:25], v[34:37], v[18:21]
	ds_read_b128 v[22:25], v97 offset:2368
	s_nop 3
	ds_read_b128 v[18:21], v97 offset:2304
	s_waitcnt lgkmcnt(0)
	v_mfma_f32_16x16x32_bf16 v[18:21], v[18:21], v[30:33], 0
	v_mfma_f32_16x16x32_bf16 v[70:73], v[22:25], v[34:37], v[18:21]
	ds_read_b128 v[22:25], v97 offset:4672
	s_nop 5
	ds_read_b128 v[18:21], v97 offset:4608
	s_waitcnt lgkmcnt(0)
	v_mfma_f32_16x16x32_bf16 v[18:21], v[18:21], v[30:33], 0
	v_mfma_f32_16x16x32_bf16 v[38:41], v[22:25], v[34:37], v[18:21]
	ds_read_b128 v[22:25], v97 offset:6976
	s_nop 5
	ds_read_b128 v[18:21], v97 offset:6912
	s_waitcnt lgkmcnt(0)
	v_mfma_f32_16x16x32_bf16 v[18:21], v[18:21], v[30:33], 0
	v_mfma_f32_16x16x32_bf16 v[58:61], v[22:25], v[34:37], v[18:21]
	ds_read_b128 v[22:25], v97 offset:9280
	s_nop 5
	ds_read_b128 v[18:21], v97 offset:9216
	s_waitcnt lgkmcnt(0)
	v_mfma_f32_16x16x32_bf16 v[18:21], v[18:21], v[30:33], 0
	v_mfma_f32_16x16x32_bf16 v[42:45], v[22:25], v[34:37], v[18:21]
	ds_read_b128 v[22:25], v97 offset:11584
	s_nop 5
	ds_read_b128 v[18:21], v97 offset:11520
	s_waitcnt lgkmcnt(0)
; #define LAS __attribute__((address_space(3)))
; __device__ __forceinline__ f32x4 mfma16(bf16x8 a, bf16x8 b, f32x4 c) { return __builtin_amdgcn_mfma_f32_16x16x32_bf16(a, b, c, 0, 0, 0); }
; __device__ __forceinline__ void attn_item(const Args& a, LAS unsigned char* lds, int layer, bool is_sample, int b, int c, int kvh, int seq_row0, int nchunks, bf16_t* proj, const int tid) {
;     ...
;         for (int kb = 0; kb < 12; ++kb) { sacc[kb] = (f32x4){0.f, 0.f, 0.f, 0.f};
; #pragma unroll
;             for (int ks = 0; ks < 2; ++ks) { const bf16x8 av = *(const LAS bf16x8*)(lds + L_KS + (16 * kb + fr) * PK + (32 * ks + 8 * fq) * 2); sacc[kb] = mfma16(av, qf[ks], sacc[kb]); } }
;         float mx = sink;
; #pragma unroll
;         for (int kb = 0; kb < 12; ++kb)
; #pragma unroll
;             for (int j = 0; j < 4; ++j) { const int kl = 16 * kb + 4 * fq + j;
;                 const float s = sacc[kb][j] + bt[g * 256 + kl - 128 - ql + 191];
;                 sacc[kb][j] = s; mx = fmaxf(mx, s); }
;         if (kmin > 0) {
;             mx = sink;
; #pragma unroll
;             for (int kb = 0; kb < 12; ++kb)
; #pragma unroll
;                 for (int j = 0; j < 4; ++j) { const int kl = 16 * kb + 4 * fq + j; if (kl < kmin) sacc[kb][j] = -INFINITY; mx = fmaxf(mx, sacc[kb][j]); }
;         }
;         mx = fmaxf(mx, __shfl_xor(mx, 16)); mx = fmaxf(mx, __shfl_xor(mx, 32));
	v_mfma_f32_16x16x32_bf16 v[18:21], v[18:21], v[30:33], 0
	v_mfma_f32_16x16x32_bf16 v[54:57], v[22:25], v[34:37], v[18:21]
	ds_read_b128 v[22:25], v97 offset:13888
	s_nop 5
	ds_read_b128 v[18:21], v97 offset:13824
	s_waitcnt lgkmcnt(0)
	v_mfma_f32_16x16x32_bf16 v[18:21], v[18:21], v[30:33], 0
	v_mfma_f32_16x16x32_bf16 v[46:49], v[22:25], v[34:37], v[18:21]
	ds_read_b128 v[22:25], v97 offset:16192
	s_nop 5
	ds_read_b128 v[18:21], v97 offset:16128
	s_waitcnt lgkmcnt(0)
	v_mfma_f32_16x16x32_bf16 v[18:21], v[18:21], v[30:33], 0
	v_mfma_f32_16x16x32_bf16 v[50:53], v[22:25], v[34:37], v[18:21]
	ds_read_b128 v[22:25], v97 offset:18496
	s_nop 5
	ds_read_b128 v[18:21], v97 offset:18432
	s_waitcnt lgkmcnt(0)
	v_mfma_f32_16x16x32_bf16 v[18:21], v[18:21], v[30:33], 0
	v_mfma_f32_16x16x32_bf16 v[18:21], v[22:25], v[34:37], v[18:21]
	ds_read_b128 v[22:25], v97 offset:20736
	s_waitcnt lgkmcnt(0)
	v_mfma_f32_16x16x32_bf16 v[22:25], v[22:25], v[30:33], 0
	v_mfma_f32_16x16x32_bf16 v[22:25], v[26:29], v[34:37], v[22:25]
	ds_read_b128 v[26:29], v97 offset:23040
	s_waitcnt lgkmcnt(0)
	v_mfma_f32_16x16x32_bf16 v[26:29], v[26:29], v[30:33], 0
	v_mfma_f32_16x16x32_bf16 v[26:29], v[74:77], v[34:37], v[26:29]
	ds_read_b128 v[74:77], v97 offset:25344
	s_waitcnt lgkmcnt(0)
	v_mfma_f32_16x16x32_bf16 v[30:33], v[74:77], v[30:33], 0
	ds_read_b128 v[74:77], v97 offset:25408
	s_waitcnt lgkmcnt(0)
	v_mfma_f32_16x16x32_bf16 v[32:35], v[74:77], v[34:37], v[30:33]
	s_nop 4
	v_sub_u32_e32 v30, v96, v146
	v_lshl_add_u32 v90, v30, 2, 0
	v_add_u32_e32 v30, 0xd0fc, v90
	ds_read2_b32 v[30:31], v30 offset1:1
	v_add_u32_e32 v36, 0xd13c, v90
	ds_read2_b32 v[36:37], v36 offset1:1
	v_add_u32_e32 v78, 0xd304, v90
	ds_read2_b32 v[78:79], v78 offset1:1
	s_waitcnt lgkmcnt(2)
	v_pk_add_f32 v[68:69], v[62:63], v[30:31]
	v_add_u32_e32 v30, 0xd104, v90
	ds_read2_b32 v[30:31], v30 offset1:1
	s_waitcnt lgkmcnt(2)
	v_pk_add_f32 v[62:63], v[70:71], v[36:37]
	v_add_u32_e32 v36, 0xd144, v90
	ds_read2_b32 v[70:71], v36 offset1:1
	v_add_u32_e32 v80, 0xd33c, v90
	ds_read2_b32 v[80:81], v80 offset1:1
	s_waitcnt lgkmcnt(2)
	v_add_f32_e32 v30, v64, v30
	v_add_u32_e32 v64, 0xd17c, v90
	s_waitcnt lgkmcnt(1)
	v_add_f32_e32 v36, v72, v70
	v_mov_b32_e32 v72, v65
	ds_read2_b32 v[64:65], v64 offset1:1
	v_add_u32_e32 v82, 0xd344, v90
	v_mov_b32_e32 v70, v31
	ds_read2_b32 v[82:83], v82 offset1:1
	v_pk_add_f32 v[70:71], v[72:73], v[70:71]
	s_waitcnt lgkmcnt(1)
	v_pk_add_f32 v[64:65], v[38:39], v[64:65]
	v_add_u32_e32 v38, 0xd184, v90
	ds_read2_b32 v[38:39], v38 offset1:1
	v_add_u32_e32 v84, 0xd37c, v90
	ds_read2_b32 v[84:85], v84 offset1:1
	v_add_u32_e32 v86, 0xd384, v90
	ds_read2_b32 v[86:87], v86 offset1:1
	s_waitcnt lgkmcnt(2)
	v_add_f32_e32 v38, v40, v38
	v_add_u32_e32 v40, 0xd1bc, v90
	ds_read2_b32 v[72:73], v40 offset1:1
	v_add_u32_e32 v40, 0xd1c4, v90
	v_add_u32_e32 v88, 0xd3bc, v90
	ds_read2_b32 v[88:89], v88 offset1:1
	v_mov_b32_e32 v37, v70
	s_waitcnt lgkmcnt(1)
	v_pk_add_f32 v[58:59], v[58:59], v[72:73]
	ds_read2_b32 v[72:73], v40 offset1:1
	v_mov_b32_e32 v31, v71
	s_waitcnt lgkmcnt(0)
	v_add_f32_e32 v40, v60, v72
	v_mov_b32_e32 v60, v41
	v_mov_b32_e32 v72, v39
	v_pk_add_f32 v[72:73], v[60:61], v[72:73]
	v_add_u32_e32 v60, 0xd1fc, v90
	ds_read2_b32 v[60:61], v60 offset1:1
	v_mov_b32_e32 v41, v72
	v_mov_b32_e32 v39, v73
	s_waitcnt lgkmcnt(0)
	v_pk_add_f32 v[60:61], v[42:43], v[60:61]
	v_add_u32_e32 v42, 0xd204, v90
	ds_read2_b32 v[42:43], v42 offset1:1
	s_waitcnt lgkmcnt(0)
	v_add_f32_e32 v42, v44, v42
	v_add_u32_e32 v44, 0xd23c, v90
	ds_read2_b32 v[74:75], v44 offset1:1
	v_add_u32_e32 v44, 0xd244, v90
	s_waitcnt lgkmcnt(0)
	v_pk_add_f32 v[54:55], v[54:55], v[74:75]
	ds_read2_b32 v[74:75], v44 offset1:1
	s_waitcnt lgkmcnt(0)
	v_add_f32_e32 v44, v56, v74
	v_mov_b32_e32 v56, v45
	v_mov_b32_e32 v74, v43
	v_pk_add_f32 v[74:75], v[56:57], v[74:75]
	v_add_u32_e32 v56, 0xd27c, v90
	ds_read2_b32 v[56:57], v56 offset1:1
	v_mov_b32_e32 v45, v74
	v_mov_b32_e32 v43, v75
	s_waitcnt lgkmcnt(0)
	v_pk_add_f32 v[56:57], v[46:47], v[56:57]
	v_add_u32_e32 v46, 0xd284, v90
	ds_read2_b32 v[46:47], v46 offset1:1
	s_waitcnt lgkmcnt(0)
	v_add_f32_e32 v46, v48, v46
	v_add_u32_e32 v48, 0xd2bc, v90
	ds_read2_b32 v[76:77], v48 offset1:1
	v_add_u32_e32 v48, 0xd2c4, v90
	s_waitcnt lgkmcnt(0)
	v_pk_add_f32 v[50:51], v[50:51], v[76:77]
	ds_read2_b32 v[76:77], v48 offset1:1
	s_waitcnt lgkmcnt(0)
	v_add_f32_e32 v48, v52, v76
	v_mov_b32_e32 v52, v49
	v_mov_b32_e32 v76, v47
	v_pk_add_f32 v[52:53], v[52:53], v[76:77]
	v_add_u32_e32 v76, 0xd2fc, v90
	v_add_u32_e32 v90, 0xd3c4, v90
	ds_read2_b32 v[76:77], v76 offset1:1
	ds_read2_b32 v[90:91], v90 offset1:1
	v_mov_b32_e32 v49, v52
	v_mov_b32_e32 v47, v53
	s_cbranch_vccnz .LBB0_479
	v_max3_f32 v147, v95, v68, v69
	v_max3_f32 v147, v147, v30, v70
	v_max3_f32 v147, v147, v62, v63
	v_max3_f32 v147, v147, v36, v71
	v_max3_f32 v147, v147, v64, v65
	v_max3_f32 v147, v147, v38, v72
	v_max3_f32 v147, v147, v58, v59
	v_max3_f32 v147, v147, v40, v73
	v_max3_f32 v147, v147, v60, v61
	v_max3_f32 v147, v147, v42, v74
	v_max3_f32 v147, v147, v54, v55
	v_max3_f32 v147, v147, v44, v75
	v_max3_f32 v147, v147, v56, v57
	v_max3_f32 v147, v147, v46, v52
	v_max3_f32 v147, v147, v50, v51
	v_max3_f32 v147, v147, v48, v53
	s_mov_b64 s[20:21], 0
